# P2: next-item K/V prefetch loads write final registers directly (no vmcnt wait + move chain); attention sink values read from a lane-held VGPR so the A-task mid-task vmcnt(0) moves to the task end
# speedup vs baseline: 1.0088x; 1.0042x over previous
; #define LAS __attribute__((address_space(3)))
;     int tid_l = threadIdx.x; asm volatile("" : "+v"(tid_l));
;     const int tid = tid_l, lane = tid & 63, wave = __builtin_amdgcn_readfirstlane(tid >> 6), qi = lane & 15, g = lane >> 4;
;     LAS unsigned char* ldsK = lds + L_K; LAS unsigned char* ldsV = lds + L_V; LAS float* tbl = (LAS float*)(lds + L_T); LAS float* pmt = (LAS float*)(lds + L_PM);
;     const int G = gridDim.x, bx = blockIdx.x;
;     const int na0 = (int)((long)bx * NITEM_A / G), nA = (int)((long)(bx + 1) * NITEM_A / G) - na0;
;     const int nb0 = (int)((long)bx * NITEM_B / G), nB = (int)((long)(bx + 1) * NITEM_B / G) - nb0;
.LBB0_134:
	s_or_b64 exec, exec, s[4:5]
	v_and_b32_e32 v242, 7, v254
	v_lshlrev_b32_e32 v242, 2, v242
	global_load_dword v241, v242, s[10:11]
	s_waitcnt vmcnt(0)
	s_mul_hi_i32 s5, s2, 0x500
	s_mul_i32 s4, s2, 0x500
	s_or_b64 s[0:1], s[4:5], s[24:25]
	v_mov_b32_e32 v147, v254
	s_mov_b32 s0, 0
	s_barrier
	s_cmp_lg_u64 s[0:1], 0
	v_readfirstlane_b32 s48, v147
	s_cbranch_scc0 .LBB0_149
	s_ashr_i32 s8, s25, 31
	s_add_u32 s0, s24, s8
	s_mov_b32 s9, s8
	s_addc_u32 s1, s25, s8
	s_xor_b64 s[12:13], s[0:1], s[8:9]
	v_cvt_f32_u32_e32 v0, s12
	v_cvt_f32_u32_e32 v1, s13
	s_sub_u32 s3, 0, s12
	s_subb_u32 s14, 0, s13
	v_fmamk_f32 v0, v1, 0x4f800000, v0
	v_rcp_f32_e32 v0, v0
	s_nop 0
	v_mul_f32_e32 v0, 0x5f7ffffc, v0
	v_mul_f32_e32 v1, 0x2f800000, v0
	v_trunc_f32_e32 v1, v1
	v_fmamk_f32 v0, v1, 0xcf800000, v0
	v_cvt_u32_f32_e32 v1, v1
	v_cvt_u32_f32_e32 v0, v0
	v_readfirstlane_b32 s15, v1
	v_readfirstlane_b32 s0, v0
	s_mul_i32 s1, s3, s15
	s_mul_hi_u32 s45, s3, s0
	s_mul_i32 s44, s14, s0
	s_add_i32 s1, s45, s1
	s_add_i32 s1, s1, s44
	s_mul_i32 s46, s3, s0
	s_mul_i32 s45, s0, s1
	s_mul_hi_u32 s47, s0, s46
	s_mul_hi_u32 s44, s0, s1
	s_add_u32 s45, s47, s45
	s_addc_u32 s44, 0, s44
	s_mul_hi_u32 s49, s15, s46
	s_mul_i32 s46, s15, s46
	s_add_u32 s45, s45, s46
	s_mul_hi_u32 s47, s15, s1
	s_addc_u32 s44, s44, s49
	s_addc_u32 s45, s47, 0
	s_mul_i32 s1, s15, s1
	s_add_u32 s1, s44, s1
	s_addc_u32 s44, 0, s45
	s_add_u32 s45, s0, s1
	s_cselect_b64 s[0:1], -1, 0
	s_cmp_lg_u64 s[0:1], 0
	s_addc_u32 s15, s15, s44
	s_mul_i32 s0, s3, s15
	s_mul_hi_u32 s1, s3, s45
	s_add_i32 s0, s1, s0
	s_mul_i32 s14, s14, s45
	s_add_i32 s0, s0, s14
	s_mul_i32 s3, s3, s45
	s_mul_hi_u32 s14, s15, s3
	s_mul_i32 s44, s15, s3
	s_mul_i32 s47, s45, s0
	s_mul_hi_u32 s3, s45, s3
	s_mul_hi_u32 s46, s45, s0
	s_add_u32 s3, s3, s47
	s_addc_u32 s46, 0, s46
	s_add_u32 s3, s3, s44
	s_mul_hi_u32 s1, s15, s0
	s_addc_u32 s3, s46, s14
	s_addc_u32 s1, s1, 0
	s_mul_i32 s0, s15, s0
	s_add_u32 s0, s3, s0
	s_addc_u32 s3, 0, s1
	s_add_u32 s44, s45, s0
	s_cselect_b64 s[0:1], -1, 0
	s_cmp_lg_u64 s[0:1], 0
	s_addc_u32 s3, s15, s3
	s_ashr_i32 s0, s5, 31
	s_add_u32 s14, s4, s0
	s_mov_b32 s1, s0
	s_addc_u32 s15, s5, s0
	s_xor_b64 s[14:15], s[14:15], s[0:1]
	s_mul_i32 s45, s14, s3
	s_mul_hi_u32 s46, s14, s44
	s_mul_hi_u32 s5, s14, s3
	s_add_u32 s45, s46, s45
	s_addc_u32 s5, 0, s5
	s_mul_hi_u32 s47, s15, s44
	s_mul_i32 s44, s15, s44
	s_add_u32 s44, s45, s44
	s_mul_hi_u32 s46, s15, s3
	s_addc_u32 s5, s5, s47
	s_addc_u32 s44, s46, 0
	s_mul_i32 s3, s15, s3
	s_add_u32 s3, s5, s3
	s_addc_u32 s5, 0, s44
	s_mul_i32 s44, s12, s5
	s_mul_hi_u32 s45, s12, s3
	s_add_i32 s44, s45, s44
	s_mul_i32 s45, s13, s3
	s_add_i32 s49, s44, s45
	s_sub_i32 s46, s15, s49
	s_mul_i32 s44, s12, s3
	s_sub_u32 s14, s14, s44
	s_cselect_b64 s[44:45], -1, 0
	s_cmp_lg_u64 s[44:45], 0
	s_subb_u32 s50, s46, s13
	s_sub_u32 s51, s14, s12
	s_cselect_b64 s[46:47], -1, 0
	s_cmp_lg_u64 s[46:47], 0
	s_subb_u32 s46, s50, 0
	s_cmp_ge_u32 s46, s13
	s_cselect_b32 s47, -1, 0
	s_cmp_ge_u32 s51, s12
	s_cselect_b32 s50, -1, 0
	s_cmp_eq_u32 s46, s13
	s_cselect_b32 s46, s50, s47
	s_add_u32 s47, s3, 1
	s_addc_u32 s50, s5, 0
	s_add_u32 s51, s3, 2
	s_addc_u32 s54, s5, 0
	s_cmp_lg_u32 s46, 0
	s_cselect_b32 s46, s51, s47
	s_cselect_b32 s47, s54, s50
	s_cmp_lg_u64 s[44:45], 0
	s_subb_u32 s15, s15, s49
	s_cmp_ge_u32 s15, s13
	s_cselect_b32 s44, -1, 0
	s_cmp_ge_u32 s14, s12
	s_cselect_b32 s12, -1, 0
	s_cmp_eq_u32 s15, s13
	s_cselect_b32 s12, s12, s44
	s_cmp_lg_u32 s12, 0
	s_cselect_b32 s13, s47, s5
	s_cselect_b32 s12, s46, s3
	s_xor_b64 s[0:1], s[0:1], s[8:9]
	s_xor_b64 s[8:9], s[12:13], s[0:1]
	s_sub_u32 s12, s8, s0
	v_cvt_f32_u32_e32 v0, s24
	s_cbranch_execnz .LBB0_137

;     ...
;         if (more) { nxt = decode(k + 1, na0, nA, nb0); ATT_ISSUE(nxt); }
.LBB0_225:
	s_mul_i32 s65, s87, s85
	s_add_i32 s1, s1, s67
	s_add_i32 s58, s86, s58
	s_add_i32 s88, s65, s69
	s_mul_hi_i32 s59, s1, 0xa00000
	s_mul_i32 s1, s1, 0xa00000
	v_add_u32_e32 v20, s58, v151
	s_add_u32 s58, s28, s1
	s_addc_u32 s59, s29, s59
	s_add_i32 s0, s0, s67
	s_mul_hi_i32 s1, s0, 0xa00000
	s_mul_i32 s0, s0, 0xa00000
	s_add_u32 s60, s28, s0
	s_addc_u32 s61, s29, s1
	v_mov_b32_e32 v57, v56
	v_mov_b64_e32 v[24:25], v[56:57]
	v_mov_b64_e32 v[26:27], v[56:57]
	v_mov_b64_e32 v[28:29], v[56:57]
	v_mov_b64_e32 v[30:31], v[56:57]
	v_mov_b64_e32 v[32:33], v[56:57]
	v_mov_b64_e32 v[34:35], v[56:57]
	v_mov_b64_e32 v[36:37], v[56:57]
	v_mov_b64_e32 v[38:39], v[56:57]
	v_mov_b64_e32 v[40:41], v[56:57]
	v_mov_b64_e32 v[42:43], v[56:57]
	v_mov_b64_e32 v[44:45], v[56:57]
	v_mov_b64_e32 v[46:47], v[56:57]
	v_mov_b64_e32 v[92:93], v[56:57]
	v_mov_b64_e32 v[94:95], v[56:57]
	v_mov_b64_e32 v[96:97], v[56:57]
	v_mov_b64_e32 v[98:99], v[56:57]
	v_mov_b64_e32 v[100:101], v[56:57]
	v_mov_b64_e32 v[102:103], v[56:57]
	v_mov_b64_e32 v[104:105], v[56:57]
	v_mov_b64_e32 v[106:107], v[56:57]
	v_mov_b64_e32 v[64:65], v[56:57]
	v_mov_b64_e32 v[66:67], v[56:57]
	v_mov_b32_e32 v58, v56
	v_mov_b32_e32 v59, v56
	v_mov_b32_e32 v60, v56
	v_mov_b32_e32 v61, v56
	v_cmp_gt_u32_e32 vcc, s74, v20
	s_and_saveexec_b64 s[62:63], vcc
	s_cbranch_execz .Lmy_iss_0
	v_add_u32_e32 v0, s88, v20
	v_ashrrev_i32_e32 v1, 31, v0
	v_lshlrev_b64 v[0:1], 7, v[0:1]
	v_lshl_or_b32 v0, v174, 1, v0
	v_lshl_add_u64 v[2:3], s[60:61], 0, v[0:1]
	v_lshl_add_u64 v[0:1], s[58:59], 0, v[0:1]
	global_load_dwordx4 v[24:27], v[0:1], off
	global_load_dwordx4 v[92:95], v[2:3], off
.Lmy_iss_0:
	s_or_b64 exec, exec, s[62:63]
	v_add_u32_e32 v22, 0x40, v20
	v_cmp_gt_u32_e32 vcc, s74, v22
	s_and_saveexec_b64 s[62:63], vcc
	s_cbranch_execz .Lmy_iss_1
	v_add_u32_e32 v0, s88, v22
	v_ashrrev_i32_e32 v1, 31, v0
	v_lshlrev_b64 v[0:1], 7, v[0:1]
	v_lshl_or_b32 v0, v174, 1, v0
	v_lshl_add_u64 v[2:3], s[60:61], 0, v[0:1]
	v_lshl_add_u64 v[0:1], s[58:59], 0, v[0:1]
	global_load_dwordx4 v[28:31], v[0:1], off
	global_load_dwordx4 v[96:99], v[2:3], off
.Lmy_iss_1:
	s_or_b64 exec, exec, s[62:63]
	v_add_u32_e32 v22, 0x80, v20
	v_cmp_gt_u32_e32 vcc, s74, v22
	s_and_saveexec_b64 s[62:63], vcc
	s_cbranch_execz .Lmy_iss_2
	v_add_u32_e32 v0, s88, v22
	v_ashrrev_i32_e32 v1, 31, v0
	v_lshlrev_b64 v[0:1], 7, v[0:1]
	v_lshl_or_b32 v0, v174, 1, v0
	v_lshl_add_u64 v[2:3], s[60:61], 0, v[0:1]
	v_lshl_add_u64 v[0:1], s[58:59], 0, v[0:1]
	global_load_dwordx4 v[32:35], v[0:1], off
	global_load_dwordx4 v[100:103], v[2:3], off
.Lmy_iss_2:
	s_or_b64 exec, exec, s[62:63]
	v_add_u32_e32 v22, 0xc0, v20
	v_cmp_gt_u32_e32 vcc, s74, v22
	s_and_saveexec_b64 s[62:63], vcc
	s_cbranch_execz .Lmy_iss_3
	v_add_u32_e32 v0, s88, v22
	v_ashrrev_i32_e32 v1, 31, v0
	v_lshlrev_b64 v[0:1], 7, v[0:1]
	v_lshl_or_b32 v0, v174, 1, v0
	v_lshl_add_u64 v[2:3], s[60:61], 0, v[0:1]
	v_lshl_add_u64 v[0:1], s[58:59], 0, v[0:1]
	global_load_dwordx4 v[36:39], v[0:1], off
	global_load_dwordx4 v[104:107], v[2:3], off
.Lmy_iss_3:
	s_or_b64 exec, exec, s[62:63]
	v_add_u32_e32 v22, 0x100, v20
	v_cmp_gt_u32_e32 vcc, s74, v22
	s_and_saveexec_b64 s[62:63], vcc
	s_cbranch_execz .Lmy_iss_4
	v_add_u32_e32 v0, s88, v22
	v_ashrrev_i32_e32 v1, 31, v0
	v_lshlrev_b64 v[0:1], 7, v[0:1]
	v_lshl_or_b32 v0, v174, 1, v0
	v_lshl_add_u64 v[2:3], s[60:61], 0, v[0:1]
	v_lshl_add_u64 v[0:1], s[58:59], 0, v[0:1]
	global_load_dwordx4 v[40:43], v[0:1], off
	global_load_dwordx4 v[64:67], v[2:3], off
.Lmy_iss_4:
	s_or_b64 exec, exec, s[62:63]
	v_add_u32_e32 v22, 0x140, v20
	v_cmp_gt_u32_e32 vcc, s74, v22
	s_and_saveexec_b64 s[62:63], vcc
	s_cbranch_execz .Lmy_iss_5
	v_add_u32_e32 v0, s88, v22
	v_ashrrev_i32_e32 v1, 31, v0
	v_lshlrev_b64 v[0:1], 7, v[0:1]
	v_lshl_or_b32 v0, v174, 1, v0
	v_lshl_add_u64 v[2:3], s[60:61], 0, v[0:1]
	v_lshl_add_u64 v[0:1], s[58:59], 0, v[0:1]
	global_load_dwordx4 v[44:47], v[0:1], off
	global_load_dwordx4 v[58:61], v[2:3], off
.Lmy_iss_5:
.LBB0_237:
	s_or_b64 exec, exec, s[62:63]
	s_mov_b32 s0, s64

; #define LAS __attribute__((address_space(3)))
;     ...
;     LAS const unsigned char* kp = ldsK + (kstart + qi) * KRS + g * 16;
;     LAS const float* pmb = pm + (kstart + 4 * g);
;     {
;         bf16x8 ka[2][2][2]; f32x4 pz[2][2];
; #pragma unroll
;         for (int j = 0; j < 2; ++j) { ka[0][j][0] = *(LAS const bf16x8*)(kp + j * 16 * KRS); ka[0][j][1] = *(LAS const bf16x8*)(kp + j * 16 * KRS + 64); pz[0][j] = *(LAS const f32x4*)(pmb + 16 * j); }
; #pragma unroll
;         for (int tp = 0; tp < NT / 2; ++tp) { const int b = tp & 1;
;             if (tp + 1 < NT / 2) {
; #pragma unroll
;                 for (int j = 0; j < 2; ++j) { const int t = 2 * (tp + 1) + j; ka[b ^ 1][j][0] = *(LAS const bf16x8*)(kp + t * 16 * KRS); ka[b ^ 1][j][1] = *(LAS const bf16x8*)(kp + t * 16 * KRS + 64); pz[b ^ 1][j] = *(LAS const f32x4*)(pmb + 16 * t); } }
;             __builtin_amdgcn_sched_barrier(0);
; #pragma unroll
;             for (int j = 0; j < 2; ++j) { f32x4 z = __builtin_amdgcn_mfma_f32_16x16x32_bf16(ka[b][j][0], qf0, pz[b][j], 0, 0, 0); s[2 * tp + j] = __builtin_amdgcn_mfma_f32_16x16x32_bf16(ka[b][j][1], qf1, z, 0, 0, 0); }
;             __builtin_amdgcn_sched_barrier(0);
;         }
;     }
;     if (has_nq) { qf0 = *(const bf16x8*)(nq + g * 8); qf1 = *(const bf16x8*)(nq + 32 + g * 8); }
;     ...
;             if (cur.isA) { const int h = (wave * 4 + i) >> 3, habs = cur.hs * 4 + h; const int qtok = cur.seq0 + cur.j0 + 16 * qt + qi; const int ks = qt < 6 ? 16 * qt : 96;
;                 attn_task<9, true>(ldsK, ldsV, tbl + h * TBL, pmt, ks, q0, q1, nq, has_nq, cur.n() + 16 * qt + qi, sink[habs] * LOG2E, (bf16*)((unsigned char*)OA + (size_t)qtok * 768 + habs * 64), nullptr, qi, g, abl);
.LBB0_243:
	v_lshl_add_u64 v[8:9], s[64:65], 0, v[144:145]
	v_lshlrev_b64 v[8:9], 7, v[8:9]
	s_or_b64 s[6:7], s[56:57], s[6:7]
	v_lshl_add_u64 v[154:155], s[28:29], 0, v[8:9]
	v_cndmask_b32_e64 v8, 0, 1, s[6:7]
	s_mov_b64 s[64:65], -1
	s_andn2_b64 vcc, exec, s[48:49]
	v_cmp_ne_u32_e64 s[6:7], 1, v8
	s_cbranch_vccnz .LBB0_247
	s_and_b32 s53, s0, 7
	s_ashr_i32 s1, s0, 3
	s_add_i32 s64, s1, s89
	s_lshl_b32 s0, s53, 4
	s_cmp_lt_u32 s53, 6
	s_cselect_b32 s53, s0, 0x60
	s_ashr_i32 s65, s64, 31
	s_lshl_b64 vcc, s[64:65], 2
	s_add_u32 vcc_lo, s10, vcc_lo
	s_addc_u32 vcc_hi, s11, vcc_hi
	v_readlane_b32 s101, v241, s64
	s_nop 1
	v_mov_b32_e32 v204, s101
	v_or_b32_e32 v8, s53, v144
	v_or_b32_e32 v205, s53, v148
	v_mad_u32_u24 v20, v8, s78, v146
	v_lshl_add_u32 v8, v205, 2, 0
	v_add_u32_e32 v172, 0x1f000, v8
	ds_read_b128 v[8:11], v20
	ds_read_b128 v[12:15], v20 offset:64
	ds_read_b128 v[16:19], v20 offset:2304
	ds_read_b128 v[48:51], v20 offset:2368
	ds_read_b128 v[52:55], v172
	ds_read_b128 v[68:71], v172 offset:64
	ds_read_b128 v[72:75], v20 offset:4608
	ds_read_b128 v[76:79], v20 offset:4672
	ds_read_b128 v[80:83], v20 offset:6912
	ds_read_b128 v[84:87], v20 offset:6976
	ds_read_b128 v[88:91], v172 offset:128
	ds_read_b128 v[108:111], v172 offset:192
	s_waitcnt lgkmcnt(7)
	v_mfma_f32_16x16x32_bf16 v[8:11], v[8:11], v[0:3], v[52:55]
	v_mfma_f32_16x16x32_bf16 v[140:143], v[12:15], v[4:7], v[8:11]
	s_waitcnt lgkmcnt(6)
	v_mfma_f32_16x16x32_bf16 v[8:11], v[16:19], v[0:3], v[68:71]
	v_mfma_f32_16x16x32_bf16 v[136:139], v[48:51], v[4:7], v[8:11]
	s_nop 6
	ds_read_b128 v[8:11], v20 offset:9216
	ds_read_b128 v[12:15], v20 offset:9280
	ds_read_b128 v[16:19], v20 offset:11520
	ds_read_b128 v[48:51], v20 offset:11584
	ds_read_b128 v[52:55], v172 offset:256
	ds_read_b128 v[68:71], v172 offset:320
	s_waitcnt lgkmcnt(7)
	v_mfma_f32_16x16x32_bf16 v[72:75], v[72:75], v[0:3], v[88:91]
	v_mfma_f32_16x16x32_bf16 v[132:135], v[76:79], v[4:7], v[72:75]
	s_waitcnt lgkmcnt(6)
	v_mfma_f32_16x16x32_bf16 v[72:75], v[80:83], v[0:3], v[108:111]
	v_mfma_f32_16x16x32_bf16 v[128:131], v[84:87], v[4:7], v[72:75]
	s_nop 6
	ds_read_b128 v[72:75], v20 offset:13824
	ds_read_b128 v[76:79], v20 offset:13888
	ds_read_b128 v[80:83], v20 offset:16128
	ds_read_b128 v[84:87], v20 offset:16192
	ds_read_b128 v[88:91], v172 offset:384
	ds_read_b128 v[108:111], v172 offset:448
	s_waitcnt lgkmcnt(7)
	v_mfma_f32_16x16x32_bf16 v[8:11], v[8:11], v[0:3], v[52:55]
	v_mfma_f32_16x16x32_bf16 v[124:127], v[12:15], v[4:7], v[8:11]
	s_waitcnt lgkmcnt(6)
	v_mfma_f32_16x16x32_bf16 v[8:11], v[16:19], v[0:3], v[68:71]
	v_mfma_f32_16x16x32_bf16 v[120:123], v[48:51], v[4:7], v[8:11]
	s_nop 6
	ds_read_b128 v[8:11], v20 offset:18432
	ds_read_b128 v[12:15], v20 offset:18496
	ds_read_b128 v[16:19], v20 offset:20736
	ds_read_b128 v[48:51], v20 offset:20800
	ds_read_b128 v[52:55], v172 offset:512
	ds_read_b128 v[68:71], v172 offset:576
	s_waitcnt lgkmcnt(7)
	v_mfma_f32_16x16x32_bf16 v[72:75], v[72:75], v[0:3], v[88:91]
	v_mfma_f32_16x16x32_bf16 v[116:119], v[76:79], v[4:7], v[72:75]
	s_waitcnt lgkmcnt(6)
	v_mfma_f32_16x16x32_bf16 v[72:75], v[80:83], v[0:3], v[108:111]
	v_mfma_f32_16x16x32_bf16 v[88:91], v[84:87], v[4:7], v[72:75]
	s_nop 6
	ds_read_b128 v[72:75], v20 offset:23040
	ds_read_b128 v[76:79], v20 offset:23104
	ds_read_b128 v[108:111], v20 offset:25344
	ds_read_b128 v[112:115], v20 offset:25408
	ds_read_b128 v[156:159], v172 offset:640
	ds_read_b128 v[160:163], v172 offset:704
	s_waitcnt lgkmcnt(7)
	v_mfma_f32_16x16x32_bf16 v[8:11], v[8:11], v[0:3], v[52:55]
	v_mfma_f32_16x16x32_bf16 v[84:87], v[12:15], v[4:7], v[8:11]
	s_waitcnt lgkmcnt(6)
	v_mfma_f32_16x16x32_bf16 v[8:11], v[16:19], v[0:3], v[68:71]
	v_mfma_f32_16x16x32_bf16 v[80:83], v[48:51], v[4:7], v[8:11]
	s_nop 6
	ds_read_b128 v[8:11], v20 offset:27648
	ds_read_b128 v[12:15], v20 offset:27712
	ds_read_b128 v[16:19], v20 offset:29952
	ds_read_b128 v[48:51], v20 offset:30016
	ds_read_b128 v[52:55], v172 offset:768
	ds_read_b128 v[164:167], v172 offset:832
	s_waitcnt lgkmcnt(7)
	v_mfma_f32_16x16x32_bf16 v[68:71], v[72:75], v[0:3], v[156:159]
	v_mfma_f32_16x16x32_bf16 v[76:79], v[76:79], v[4:7], v[68:71]
	s_waitcnt lgkmcnt(6)
	v_mfma_f32_16x16x32_bf16 v[68:71], v[108:111], v[0:3], v[160:163]
	v_mfma_f32_16x16x32_bf16 v[72:75], v[112:115], v[4:7], v[68:71]
	ds_read_b128 v[108:111], v20 offset:32256
	ds_read_b128 v[112:115], v20 offset:32320
	ds_read_b128 v[156:159], v20 offset:34560
	ds_read_b128 v[160:163], v20 offset:34624
	ds_read_b128 v[168:171], v172 offset:896
	ds_read_b128 v[206:209], v172 offset:960
	s_waitcnt lgkmcnt(7)
	v_mfma_f32_16x16x32_bf16 v[8:11], v[8:11], v[0:3], v[52:55]
	v_mfma_f32_16x16x32_bf16 v[68:71], v[12:15], v[4:7], v[8:11]
	s_waitcnt lgkmcnt(6)
	v_mfma_f32_16x16x32_bf16 v[8:11], v[16:19], v[0:3], v[164:167]
	v_mfma_f32_16x16x32_bf16 v[52:55], v[48:51], v[4:7], v[8:11]
	s_nop 6
	ds_read_b128 v[8:11], v20 offset:36864
	ds_read_b128 v[12:15], v20 offset:36928
	ds_read_b128 v[164:167], v20 offset:39168
	ds_read_b128 v[210:213], v20 offset:39232
	ds_read_b128 v[214:217], v172 offset:1024
	ds_read_b128 v[218:221], v172 offset:1088
	s_waitcnt lgkmcnt(7)
	v_mfma_f32_16x16x32_bf16 v[16:19], v[108:111], v[0:3], v[168:171]
	v_mfma_f32_16x16x32_bf16 v[48:51], v[112:115], v[4:7], v[16:19]
	s_waitcnt lgkmcnt(6)
	v_mfma_f32_16x16x32_bf16 v[16:19], v[156:159], v[0:3], v[206:209]
	v_mfma_f32_16x16x32_bf16 v[16:19], v[160:163], v[4:7], v[16:19]
	s_waitcnt lgkmcnt(1)
	v_mfma_f32_16x16x32_bf16 v[8:11], v[8:11], v[0:3], v[214:217]
	v_mfma_f32_16x16x32_bf16 v[12:15], v[12:15], v[4:7], v[8:11]
	s_waitcnt lgkmcnt(0)
	v_mfma_f32_16x16x32_bf16 v[8:11], v[164:167], v[0:3], v[218:221]
	v_mfma_f32_16x16x32_bf16 v[8:11], v[210:213], v[4:7], v[8:11]
	v_mov_b64_e32 v[114:115], v[6:7]
	v_mov_b64_e32 v[110:111], v[2:3]
	s_and_b64 vcc, exec, s[6:7]
	v_mov_b64_e32 v[112:113], v[4:5]
	v_mov_b64_e32 v[108:109], v[0:1]
	s_cbranch_vccnz .LBB0_246
	v_lshlrev_b32_e32 v20, 1, v62
	v_lshl_add_u64 v[112:113], v[154:155], 0, v[20:21]
	global_load_dwordx4 v[108:111], v[112:113], off
	s_nop 0
	global_load_dwordx4 v[112:115], v[112:113], off offset:64
; #define LAS __attribute__((address_space(3)))
;     ...
;     constexpr float C = 0.125f * LOG2E; const float NEG = -__builtin_inff();
;     LAS const float* tb = tbl + (kstart + 4 * g - qrel + TBL / 2);
;     float m = NEG;
;     {
;         float tv[2][8];
; #pragma unroll
;         for (int i = 0; i < 8; ++i) tv[0][i] = tb[16 * (i >> 2) + (i & 3)];
; #pragma unroll
;         for (int tp = 0; tp < NT / 2; ++tp) { const int b = tp & 1;
;             if (tp + 1 < NT / 2) {
; #pragma unroll
;                 for (int i = 0; i < 8; ++i) tv[b ^ 1][i] = tb[16 * (2 * (tp + 1) + (i >> 2)) + (i & 3)]; }
;             __builtin_amdgcn_sched_barrier(0);
; #pragma unroll
;             for (int i = 0; i < 8; ++i) { const int t = 2 * tp + (i >> 2), r = i & 3; const float v = s[t][r] * C + tv[b][i]; s[t][r] = v; m = fmaxf(m, v); }
;             __builtin_amdgcn_sched_barrier(0);
;         }
;     }
;     m = fmaxf(m, __shfl_xor(m, 16)); m = fmaxf(m, __shfl_xor(m, 32));
.LBB0_246:
	s_mulk_i32 s1, 0xa00
	s_add_i32 s1, s1, 0
	v_or_b32_e32 v158, s0, v144
	s_add_i32 s1, s1, 0x1c800
	v_sub_u32_e32 v158, v205, v158
	v_lshl_add_u32 v177, v158, 2, s1
	ds_read2_b32 v[172:173], v177 offset0:192 offset1:193
	ds_read2_b32 v[170:171], v177 offset0:194 offset1:195
	ds_read2_b32 v[168:169], v177 offset0:208 offset1:209
	ds_read2_b32 v[166:167], v177 offset0:210 offset1:211
	ds_read2_b32 v[164:165], v177 offset0:224 offset1:225
	ds_read2_b32 v[162:163], v177 offset0:226 offset1:227
	ds_read2_b32 v[160:161], v177 offset0:240 offset1:241
	ds_read2_b32 v[158:159], v177 offset0:242 offset1:243
	v_add_u32_e32 v20, s0, v201
	v_mov_b64_e32 v[156:157], s[16:17]
	s_movk_i32 s0, 0x300
	v_mad_i64_i32 v[156:157], s[0:1], v20, s0, v[156:157]
	s_lshl_b32 s0, s64, 6
	s_ashr_i32 s1, s0, 31
	v_mul_f32_e32 v176, 0x3fb8aa3b, v204
	v_lshl_add_u64 v[156:157], v[156:157], 0, s[0:1]
	s_waitcnt lgkmcnt(7)
	v_fmamk_f32 v20, v140, 0x3e38aa3b, v172
	v_fmac_f32_e32 v173, 0x3e38aa3b, v141
	v_max3_f32 v140, v20, s81, v173
	s_waitcnt lgkmcnt(6)
	v_fmamk_f32 v170, v142, 0x3e38aa3b, v170
	v_fmac_f32_e32 v171, 0x3e38aa3b, v143
	v_max3_f32 v140, v140, v170, v171
	s_waitcnt lgkmcnt(5)
	v_fmamk_f32 v168, v136, 0x3e38aa3b, v168
	v_fmac_f32_e32 v169, 0x3e38aa3b, v137
	v_max3_f32 v136, v140, v168, v169
	s_waitcnt lgkmcnt(4)
	v_fmamk_f32 v166, v138, 0x3e38aa3b, v166
	v_fmac_f32_e32 v167, 0x3e38aa3b, v139
	v_max3_f32 v172, v136, v166, v167
	v_add_u32_e32 v136, 0x400, v177
	v_add_u32_e32 v137, 0x408, v177
	v_add_u32_e32 v138, 0x440, v177
	v_add_u32_e32 v196, 0x448, v177
	ds_read2_b32 v[142:143], v136 offset1:1
	ds_read2_b32 v[140:141], v137 offset1:1
	ds_read2_b32 v[138:139], v138 offset1:1
	ds_read2_b32 v[136:137], v196 offset1:1
	s_waitcnt lgkmcnt(7)
	v_fmamk_f32 v164, v132, 0x3e38aa3b, v164
	v_fmac_f32_e32 v165, 0x3e38aa3b, v133
	v_max3_f32 v132, v172, v164, v165
	s_waitcnt lgkmcnt(6)
	v_fmamk_f32 v162, v134, 0x3e38aa3b, v162
	v_fmac_f32_e32 v163, 0x3e38aa3b, v135
	v_max3_f32 v132, v132, v162, v163
	s_waitcnt lgkmcnt(5)
	v_fmamk_f32 v160, v128, 0x3e38aa3b, v160
	v_fmac_f32_e32 v161, 0x3e38aa3b, v129
	v_max3_f32 v128, v132, v160, v161
	s_waitcnt lgkmcnt(4)
	v_fmamk_f32 v158, v130, 0x3e38aa3b, v158
	v_fmac_f32_e32 v159, 0x3e38aa3b, v131
	v_max3_f32 v172, v128, v158, v159
	v_add_u32_e32 v128, 0x480, v177
	v_add_u32_e32 v129, 0x488, v177
	v_add_u32_e32 v130, 0x4c0, v177
	v_add_u32_e32 v196, 0x4c8, v177
	ds_read2_b32 v[134:135], v128 offset1:1
	ds_read2_b32 v[132:133], v129 offset1:1
	ds_read2_b32 v[130:131], v130 offset1:1
	ds_read2_b32 v[128:129], v196 offset1:1
	s_waitcnt lgkmcnt(7)
	v_fmamk_f32 v142, v124, 0x3e38aa3b, v142
	v_fmac_f32_e32 v143, 0x3e38aa3b, v125
	v_max3_f32 v124, v172, v142, v143
	s_waitcnt lgkmcnt(6)
	v_fmamk_f32 v140, v126, 0x3e38aa3b, v140
	v_fmac_f32_e32 v141, 0x3e38aa3b, v127
	v_max3_f32 v124, v124, v140, v141
	s_waitcnt lgkmcnt(5)
	v_fmamk_f32 v138, v120, 0x3e38aa3b, v138
	v_fmac_f32_e32 v139, 0x3e38aa3b, v121
	v_max3_f32 v120, v124, v138, v139
	s_waitcnt lgkmcnt(4)
	v_fmamk_f32 v136, v122, 0x3e38aa3b, v136
	v_fmac_f32_e32 v137, 0x3e38aa3b, v123
	v_max3_f32 v172, v120, v136, v137
	v_add_u32_e32 v120, 0x500, v177
	v_add_u32_e32 v121, 0x508, v177
	v_add_u32_e32 v122, 0x540, v177
	v_add_u32_e32 v196, 0x548, v177
	ds_read2_b32 v[126:127], v120 offset1:1
	ds_read2_b32 v[124:125], v121 offset1:1
	ds_read2_b32 v[122:123], v122 offset1:1
	ds_read2_b32 v[120:121], v196 offset1:1
	s_waitcnt lgkmcnt(7)
	v_fmamk_f32 v134, v116, 0x3e38aa3b, v134
	v_fmac_f32_e32 v135, 0x3e38aa3b, v117
	v_max3_f32 v116, v172, v134, v135
	s_waitcnt lgkmcnt(6)
	v_fmamk_f32 v132, v118, 0x3e38aa3b, v132
	v_fmac_f32_e32 v133, 0x3e38aa3b, v119
	v_max3_f32 v116, v116, v132, v133
	s_waitcnt lgkmcnt(5)
	v_fmamk_f32 v130, v88, 0x3e38aa3b, v130
	v_fmac_f32_e32 v131, 0x3e38aa3b, v89
	v_max3_f32 v88, v116, v130, v131
	s_waitcnt lgkmcnt(4)
	v_fmamk_f32 v128, v90, 0x3e38aa3b, v128
	v_fmac_f32_e32 v129, 0x3e38aa3b, v91
	v_max3_f32 v172, v88, v128, v129
	v_add_u32_e32 v88, 0x580, v177
	v_add_u32_e32 v89, 0x588, v177
	v_add_u32_e32 v90, 0x5c0, v177
	v_add_u32_e32 v196, 0x5c8, v177
	ds_read2_b32 v[118:119], v88 offset1:1
	ds_read2_b32 v[116:117], v89 offset1:1
	ds_read2_b32 v[90:91], v90 offset1:1
	ds_read2_b32 v[88:89], v196 offset1:1
	s_waitcnt lgkmcnt(7)
	v_fmamk_f32 v126, v84, 0x3e38aa3b, v126
	v_fmac_f32_e32 v127, 0x3e38aa3b, v85
	v_max3_f32 v84, v172, v126, v127
	s_waitcnt lgkmcnt(6)
	v_fmamk_f32 v124, v86, 0x3e38aa3b, v124
	v_fmac_f32_e32 v125, 0x3e38aa3b, v87
	v_max3_f32 v84, v84, v124, v125
	s_waitcnt lgkmcnt(5)
	v_fmamk_f32 v122, v80, 0x3e38aa3b, v122
	v_fmac_f32_e32 v123, 0x3e38aa3b, v81
	v_max3_f32 v80, v84, v122, v123
	s_waitcnt lgkmcnt(4)
	v_fmamk_f32 v120, v82, 0x3e38aa3b, v120
	v_fmac_f32_e32 v121, 0x3e38aa3b, v83
	v_max3_f32 v172, v80, v120, v121
	v_add_u32_e32 v80, 0x600, v177
	v_add_u32_e32 v81, 0x608, v177
	v_add_u32_e32 v82, 0x640, v177
	v_add_u32_e32 v196, 0x648, v177
	ds_read2_b32 v[86:87], v80 offset1:1
	ds_read2_b32 v[84:85], v81 offset1:1
	ds_read2_b32 v[82:83], v82 offset1:1
	ds_read2_b32 v[80:81], v196 offset1:1
	s_waitcnt lgkmcnt(7)
	v_fmamk_f32 v118, v76, 0x3e38aa3b, v118
	v_fmac_f32_e32 v119, 0x3e38aa3b, v77
	v_max3_f32 v76, v172, v118, v119
	s_waitcnt lgkmcnt(6)
	v_fmamk_f32 v116, v78, 0x3e38aa3b, v116
	v_fmac_f32_e32 v117, 0x3e38aa3b, v79
	v_max3_f32 v76, v76, v116, v117
	s_waitcnt lgkmcnt(5)
	v_fmamk_f32 v90, v72, 0x3e38aa3b, v90
	v_fmac_f32_e32 v91, 0x3e38aa3b, v73
	v_max3_f32 v72, v76, v90, v91
	s_waitcnt lgkmcnt(4)
;     ...
;             for (int i = 0; i < 8; ++i) { const int t = 2 * tp + (i >> 2), r = i & 3; const float v = s[t][r] * C + tv[b][i]; s[t][r] = v; m = fmaxf(m, v); }
;             __builtin_amdgcn_sched_barrier(0);
;         }
;     }
;     m = fmaxf(m, __shfl_xor(m, 16)); m = fmaxf(m, __shfl_xor(m, 32));
;     if (IS_A) m = fmaxf(m, sink2);
;     float sum = 0.f;
; #pragma unroll
;     for (int t = 0; t < NT; ++t)
; #pragma unroll
;         for (int r = 0; r < 4; ++r) { const float p = __builtin_amdgcn_exp2f(s[t][r] - m); s[t][r] = p; sum += p; }
;     sum += __shfl_xor(sum, 16); sum += __shfl_xor(sum, 32);
;     if (IS_A) sum += __builtin_amdgcn_exp2f(sink2 - m);
	v_fmamk_f32 v88, v74, 0x3e38aa3b, v88
	v_fmac_f32_e32 v89, 0x3e38aa3b, v75
	v_max3_f32 v172, v72, v88, v89
	v_add_u32_e32 v72, 0x680, v177
	v_add_u32_e32 v73, 0x688, v177
	v_add_u32_e32 v74, 0x6c0, v177
	v_add_u32_e32 v196, 0x6c8, v177
	ds_read2_b32 v[78:79], v72 offset1:1
	ds_read2_b32 v[76:77], v73 offset1:1
	ds_read2_b32 v[74:75], v74 offset1:1
	ds_read2_b32 v[72:73], v196 offset1:1
	s_waitcnt lgkmcnt(7)
	v_fmamk_f32 v86, v68, 0x3e38aa3b, v86
	v_fmac_f32_e32 v87, 0x3e38aa3b, v69
	v_max3_f32 v68, v172, v86, v87
	s_waitcnt lgkmcnt(6)
	v_fmamk_f32 v84, v70, 0x3e38aa3b, v84
	v_fmac_f32_e32 v85, 0x3e38aa3b, v71
	v_max3_f32 v68, v68, v84, v85
	s_waitcnt lgkmcnt(5)
	v_fmamk_f32 v82, v52, 0x3e38aa3b, v82
	v_fmac_f32_e32 v83, 0x3e38aa3b, v53
	v_max3_f32 v52, v68, v82, v83
	s_waitcnt lgkmcnt(4)
	v_fmamk_f32 v80, v54, 0x3e38aa3b, v80
	v_fmac_f32_e32 v81, 0x3e38aa3b, v55
	v_max3_f32 v172, v52, v80, v81
	v_add_u32_e32 v52, 0x700, v177
	v_add_u32_e32 v53, 0x708, v177
	v_add_u32_e32 v54, 0x740, v177
	v_add_u32_e32 v177, 0x748, v177
	ds_read2_b32 v[70:71], v52 offset1:1
	ds_read2_b32 v[68:69], v53 offset1:1
	ds_read2_b32 v[54:55], v54 offset1:1
	ds_read2_b32 v[52:53], v177 offset1:1
	s_waitcnt lgkmcnt(7)
	v_fmamk_f32 v48, v48, 0x3e38aa3b, v78
	v_fmac_f32_e32 v79, 0x3e38aa3b, v49
	v_max3_f32 v49, v172, v48, v79
	s_waitcnt lgkmcnt(6)
	v_fmamk_f32 v50, v50, 0x3e38aa3b, v76
	v_fmac_f32_e32 v77, 0x3e38aa3b, v51
	v_max3_f32 v49, v49, v50, v77
	s_waitcnt lgkmcnt(5)
	v_fmamk_f32 v16, v16, 0x3e38aa3b, v74
	v_fmac_f32_e32 v75, 0x3e38aa3b, v17
	v_max3_f32 v17, v49, v16, v75
	s_waitcnt lgkmcnt(4)
	v_fmamk_f32 v18, v18, 0x3e38aa3b, v72
	v_fmac_f32_e32 v73, 0x3e38aa3b, v19
	v_max3_f32 v17, v17, v18, v73
	s_waitcnt lgkmcnt(3)
	v_fmamk_f32 v12, v12, 0x3e38aa3b, v70
	v_fmac_f32_e32 v71, 0x3e38aa3b, v13
	v_max3_f32 v13, v17, v12, v71
	s_waitcnt lgkmcnt(2)
	v_fmamk_f32 v14, v14, 0x3e38aa3b, v68
	v_fmac_f32_e32 v69, 0x3e38aa3b, v15
	v_max3_f32 v13, v13, v14, v69
	s_waitcnt lgkmcnt(1)
	v_fmamk_f32 v15, v8, 0x3e38aa3b, v54
	v_fmac_f32_e32 v55, 0x3e38aa3b, v9
	v_max3_f32 v8, v13, v15, v55
	s_waitcnt lgkmcnt(0)
	v_fmamk_f32 v9, v10, 0x3e38aa3b, v52
	v_fmac_f32_e32 v53, 0x3e38aa3b, v11
	v_max3_f32 v8, v8, v9, v53
	v_and_b32_e32 v11, 64, v199
	v_xor_b32_e32 v10, 16, v199
	v_add_u32_e32 v11, 64, v11
	v_cmp_lt_i32_e32 vcc, v10, v11
	v_xor_b32_e32 v17, 32, v199
	s_nop 0
	v_cndmask_b32_e32 v10, v199, v10, vcc
	v_lshlrev_b32_e32 v10, 2, v10
	ds_bpermute_b32 v13, v10, v8
	v_cmp_lt_i32_e32 vcc, v17, v11
	s_waitcnt lgkmcnt(0)
	v_max_f32_e32 v13, v13, v13
	v_cndmask_b32_e32 v11, v199, v17, vcc
	v_max_f32_e32 v8, v8, v13
	v_lshlrev_b32_e32 v11, 2, v11
	ds_bpermute_b32 v13, v11, v8
	s_waitcnt lgkmcnt(0)
	v_max3_f32 v8, v8, v13, v176
	v_sub_f32_e32 v13, v20, v8
	v_sub_f32_e32 v17, v173, v8
	v_exp_f32_e32 v19, v13
	v_exp_f32_e32 v20, v17
	v_sub_f32_e32 v13, v170, v8
	v_exp_f32_e32 v170, v13
	v_sub_f32_e32 v13, v171, v8
	v_exp_f32_e32 v171, v13
	v_sub_f32_e32 v17, v168, v8
	v_add_f32_e32 v13, 0, v19
	v_exp_f32_e32 v168, v17
	v_sub_f32_e32 v17, v169, v8
	v_add_f32_e32 v13, v20, v13
	v_exp_f32_e32 v169, v17
	v_sub_f32_e32 v17, v166, v8
	v_add_f32_e32 v13, v170, v13
	v_exp_f32_e32 v166, v17
	v_sub_f32_e32 v17, v167, v8
	v_add_f32_e32 v13, v171, v13
	v_exp_f32_e32 v167, v17
	v_sub_f32_e32 v17, v164, v8
	v_add_f32_e32 v13, v168, v13
	v_exp_f32_e32 v164, v17
	v_sub_f32_e32 v17, v165, v8
	v_add_f32_e32 v13, v169, v13
	v_exp_f32_e32 v165, v17
	v_sub_f32_e32 v17, v162, v8
	v_add_f32_e32 v13, v166, v13
	v_exp_f32_e32 v162, v17
	v_sub_f32_e32 v17, v163, v8
	v_add_f32_e32 v13, v167, v13
	v_exp_f32_e32 v163, v17
	v_sub_f32_e32 v17, v160, v8
	v_add_f32_e32 v13, v164, v13
	v_exp_f32_e32 v160, v17
	v_sub_f32_e32 v17, v161, v8
	v_add_f32_e32 v13, v165, v13
	v_exp_f32_e32 v161, v17
	v_sub_f32_e32 v17, v158, v8
	v_add_f32_e32 v13, v162, v13
	v_exp_f32_e32 v158, v17
	v_sub_f32_e32 v17, v159, v8
	v_add_f32_e32 v13, v163, v13
	v_exp_f32_e32 v159, v17
	v_sub_f32_e32 v17, v142, v8
	v_add_f32_e32 v13, v160, v13
	v_exp_f32_e32 v142, v17
	v_sub_f32_e32 v17, v143, v8
	v_add_f32_e32 v13, v161, v13
	v_exp_f32_e32 v143, v17
	v_sub_f32_e32 v17, v140, v8
	v_add_f32_e32 v13, v158, v13
	v_exp_f32_e32 v140, v17
	v_sub_f32_e32 v17, v141, v8
	v_add_f32_e32 v13, v159, v13
	v_exp_f32_e32 v141, v17
	v_sub_f32_e32 v17, v138, v8
	v_add_f32_e32 v13, v142, v13
	v_exp_f32_e32 v138, v17
	v_sub_f32_e32 v17, v139, v8
	v_add_f32_e32 v13, v143, v13
	v_exp_f32_e32 v139, v17
	v_sub_f32_e32 v17, v136, v8
	v_add_f32_e32 v13, v140, v13
	v_exp_f32_e32 v136, v17
	v_sub_f32_e32 v17, v137, v8
	v_add_f32_e32 v13, v141, v13
	v_exp_f32_e32 v137, v17
	v_sub_f32_e32 v17, v134, v8
	v_add_f32_e32 v13, v138, v13
	v_exp_f32_e32 v134, v17
	v_sub_f32_e32 v17, v135, v8
	v_add_f32_e32 v13, v139, v13
	v_exp_f32_e32 v135, v17
	v_sub_f32_e32 v17, v132, v8
	v_add_f32_e32 v13, v136, v13
	v_exp_f32_e32 v132, v17
	v_sub_f32_e32 v17, v133, v8
	v_add_f32_e32 v13, v137, v13
	v_exp_f32_e32 v133, v17
	v_sub_f32_e32 v17, v130, v8
	v_add_f32_e32 v13, v134, v13
	v_exp_f32_e32 v130, v17
	v_sub_f32_e32 v17, v131, v8
	v_add_f32_e32 v13, v135, v13
	v_exp_f32_e32 v131, v17
	v_sub_f32_e32 v17, v128, v8
	v_add_f32_e32 v13, v132, v13
	v_exp_f32_e32 v128, v17
	v_sub_f32_e32 v17, v129, v8
	v_add_f32_e32 v13, v133, v13
	v_exp_f32_e32 v129, v17
	v_sub_f32_e32 v17, v126, v8
	v_add_f32_e32 v13, v130, v13
	v_exp_f32_e32 v172, v17
	v_sub_f32_e32 v17, v127, v8
	v_add_f32_e32 v13, v131, v13
	v_exp_f32_e32 v173, v17
	v_sub_f32_e32 v17, v124, v8
	v_add_f32_e32 v13, v128, v13
	v_exp_f32_e32 v176, v17
	v_sub_f32_e32 v17, v125, v8
	v_add_f32_e32 v13, v129, v13
	v_exp_f32_e32 v177, v17
; #define LAS __attribute__((address_space(3)))
; __device__ __forceinline__ unsigned cvtpk(float lo, float hi) { return pg8::cvt_pk_bf16(lo, hi); }
; __device__ __forceinline__ s16x4 vtr(LAS const unsigned char* p) { return __builtin_bit_cast(s16x4, __builtin_amdgcn_ds_read_tr16_b64_v4i16((LAS s16x4*)p)); }
;     ...
;     for (int t = 0; t < NT; ++t)
; #pragma unroll
;         for (int r = 0; r < 4; ++r) { const float p = __builtin_amdgcn_exp2f(s[t][r] - m); s[t][r] = p; sum += p; }
;     sum += __shfl_xor(sum, 16); sum += __shfl_xor(sum, 32);
;     if (IS_A) sum += __builtin_amdgcn_exp2f(sink2 - m);
;     const float inv = __builtin_amdgcn_rcpf(sum);
;     f32x4 o[4];
; #pragma unroll
;     for (int d = 0; d < 4; ++d) o[d] = (f32x4){0.f, 0.f, 0.f, 0.f};
;     LAS const unsigned char* vp = ldsV + (kstart + 4 * g + (qi >> 2)) * VRS + (qi & 3) * 8;
;     {
;         s16x4 vl[2][4], vh[2][4];
; #pragma unroll
;         for (int d = 0; d < 4; ++d) { vl[0][d] = vtr(vp + d * 32); vh[0][d] = vtr(vp + 16 * VRS + d * 32); }
; #pragma unroll
;         for (int c = 0; c < NCH; ++c) { const int b = c & 1;
;             if (c + 1 < NCH) {
; #pragma unroll
;                 for (int d = 0; d < 4; ++d) { vl[b ^ 1][d] = vtr(vp + (32 * (c + 1)) * VRS + d * 32); vh[b ^ 1][d] = vtr(vp + (32 * (c + 1) + 16) * VRS + d * 32); } }
;             v4u pw; pw.x = cvtpk(s[2 * c][0], s[2 * c][1]); pw.y = cvtpk(s[2 * c][2], s[2 * c][3]); pw.z = cvtpk(s[2 * c + 1][0], s[2 * c + 1][1]); pw.w = cvtpk(s[2 * c + 1][2], s[2 * c + 1][3]);
;             const bf16x8 pb = __builtin_bit_cast(bf16x8, pw);
;             __builtin_amdgcn_sched_barrier(0);
; #pragma unroll
;             for (int d = 0; d < 4; ++d) { const s16x4 lo = vl[b][d], hi = vh[b][d];
;                 const bf16x8 va = (bf16x8){lo[0], lo[1], lo[2], lo[3], hi[0], hi[1], hi[2], hi[3]};
;                 o[d] = __builtin_amdgcn_mfma_f32_16x16x32_bf16(va, pb, o[d], 0, 0, 0); }
	v_sub_f32_e32 v17, v122, v8
	v_add_f32_e32 v13, v172, v13
	v_exp_f32_e32 v196, v17
	v_sub_f32_e32 v17, v123, v8
	v_add_f32_e32 v13, v173, v13
	v_exp_f32_e32 v206, v17
	v_sub_f32_e32 v17, v120, v8
	v_add_f32_e32 v13, v176, v13
	v_exp_f32_e32 v207, v17
	v_sub_f32_e32 v17, v121, v8
	v_add_f32_e32 v13, v177, v13
	v_exp_f32_e32 v208, v17
	v_sub_f32_e32 v17, v118, v8
	v_add_f32_e32 v13, v196, v13
	v_exp_f32_e32 v209, v17
	v_sub_f32_e32 v17, v119, v8
	v_add_f32_e32 v13, v206, v13
	v_exp_f32_e32 v210, v17
	v_sub_f32_e32 v17, v116, v8
	v_add_f32_e32 v13, v207, v13
	v_exp_f32_e32 v211, v17
	v_sub_f32_e32 v17, v117, v8
	v_add_f32_e32 v13, v208, v13
	v_exp_f32_e32 v212, v17
	v_sub_f32_e32 v17, v90, v8
	v_add_f32_e32 v13, v209, v13
	v_exp_f32_e32 v213, v17
	v_sub_f32_e32 v17, v91, v8
	v_add_f32_e32 v13, v210, v13
	v_exp_f32_e32 v214, v17
	v_sub_f32_e32 v17, v88, v8
	v_add_f32_e32 v13, v211, v13
	v_exp_f32_e32 v215, v17
	v_sub_f32_e32 v17, v89, v8
	v_add_f32_e32 v13, v212, v13
	v_exp_f32_e32 v216, v17
	v_sub_f32_e32 v17, v86, v8
	v_add_f32_e32 v13, v213, v13
	v_exp_f32_e32 v217, v17
	v_sub_f32_e32 v17, v87, v8
	v_add_f32_e32 v13, v214, v13
	v_exp_f32_e32 v218, v17
	v_sub_f32_e32 v17, v84, v8
	v_add_f32_e32 v13, v215, v13
	v_exp_f32_e32 v219, v17
	v_sub_f32_e32 v17, v85, v8
	v_add_f32_e32 v13, v216, v13
	v_exp_f32_e32 v220, v17
	v_sub_f32_e32 v17, v82, v8
	v_add_f32_e32 v13, v217, v13
	v_exp_f32_e32 v221, v17
	v_sub_f32_e32 v17, v83, v8
	v_add_f32_e32 v13, v218, v13
	v_exp_f32_e32 v222, v17
	v_sub_f32_e32 v17, v80, v8
	v_add_f32_e32 v13, v219, v13
	v_exp_f32_e32 v223, v17
	v_sub_f32_e32 v17, v81, v8
	v_add_f32_e32 v13, v220, v13
	v_exp_f32_e32 v224, v17
	v_sub_f32_e32 v17, v48, v8
	v_add_f32_e32 v13, v221, v13
	v_exp_f32_e32 v225, v17
	v_sub_f32_e32 v17, v79, v8
	v_add_f32_e32 v13, v222, v13
	v_exp_f32_e32 v226, v17
	v_sub_f32_e32 v17, v50, v8
	v_add_f32_e32 v13, v223, v13
	v_exp_f32_e32 v227, v17
	v_sub_f32_e32 v17, v77, v8
	v_add_f32_e32 v13, v224, v13
	v_exp_f32_e32 v228, v17
	v_sub_f32_e32 v16, v16, v8
	v_add_f32_e32 v13, v225, v13
	v_exp_f32_e32 v229, v16
	v_sub_f32_e32 v16, v75, v8
	v_add_f32_e32 v13, v226, v13
	v_exp_f32_e32 v230, v16
	v_sub_f32_e32 v16, v18, v8
	v_add_f32_e32 v13, v227, v13
	v_exp_f32_e32 v18, v16
	v_sub_f32_e32 v16, v73, v8
	v_add_f32_e32 v13, v228, v13
	v_exp_f32_e32 v231, v16
	v_sub_f32_e32 v12, v12, v8
	v_add_f32_e32 v13, v229, v13
	v_exp_f32_e32 v232, v12
	v_add_f32_e32 v13, v230, v13
	v_sub_f32_e32 v12, v71, v8
	v_add_f32_e32 v13, v18, v13
	v_exp_f32_e32 v233, v12
	v_sub_f32_e32 v12, v14, v8
	v_add_f32_e32 v13, v231, v13
	v_exp_f32_e32 v234, v12
	v_sub_f32_e32 v12, v69, v8
	v_exp_f32_e32 v235, v12
	v_add_f32_e32 v12, v232, v13
	v_sub_f32_e32 v13, v15, v8
	v_exp_f32_e32 v236, v13
	v_sub_f32_e32 v13, v55, v8
	v_add_f32_e32 v12, v233, v12
	v_exp_f32_e32 v237, v13
	v_sub_f32_e32 v9, v9, v8
	v_add_f32_e32 v12, v234, v12
	v_exp_f32_e32 v9, v9
	v_sub_f32_e32 v13, v53, v8
	v_add_f32_e32 v12, v235, v12
	v_exp_f32_e32 v238, v13
	v_add_f32_e32 v12, v236, v12
	v_add_f32_e32 v12, v237, v12
	v_add_f32_e32 v12, v9, v12
	v_add_f32_e32 v12, v238, v12
	ds_bpermute_b32 v10, v10, v12
	v_cvt_pk_bf16_f32 v84, v19, v20
	v_cvt_pk_bf16_f32 v85, v170, v171
	v_cvt_pk_bf16_f32 v86, v168, v169
	v_cvt_pk_bf16_f32 v87, v166, v167
	s_waitcnt lgkmcnt(0)
	v_add_f32_e32 v239, v12, v10
	v_or_b32_e32 v10, v205, v178
	v_mad_u32_u24 v82, v10, s79, v150
	ds_bpermute_b32 v240, v11, v239
	v_add_u32_e32 v205, 0xd800, v82
	ds_read_b64_tr_b16 v[10:11], v82 offset:55296
	ds_read_b64_tr_b16 v[14:15], v82 offset:55328
	ds_read_b64_tr_b16 v[48:49], v82 offset:55360
	ds_read_b64_tr_b16 v[52:53], v82 offset:55392
	ds_read_b64_tr_b16 v[12:13], v82 offset:57856
	ds_read_b64_tr_b16 v[16:17], v82 offset:57888
	ds_read_b64_tr_b16 v[50:51], v82 offset:57920
	ds_read_b64_tr_b16 v[54:55], v82 offset:57952
	ds_read_b64_tr_b16 v[68:69], v82 offset:60416
	ds_read_b64_tr_b16 v[72:73], v82 offset:60448
	ds_read_b64_tr_b16 v[76:77], v82 offset:60480
	ds_read_b64_tr_b16 v[80:81], v82 offset:60512
	ds_read_b64_tr_b16 v[70:71], v82 offset:62976
	ds_read_b64_tr_b16 v[74:75], v82 offset:63008
	ds_read_b64_tr_b16 v[78:79], v82 offset:63040
	ds_read_b64_tr_b16 v[82:83], v82 offset:63072
	s_waitcnt lgkmcnt(11)
	v_mfma_f32_16x16x32_bf16 v[10:13], v[10:13], v[84:87], 0
	s_waitcnt lgkmcnt(10)
	v_mfma_f32_16x16x32_bf16 v[14:17], v[14:17], v[84:87], 0
	s_waitcnt lgkmcnt(9)
	v_mfma_f32_16x16x32_bf16 v[48:51], v[48:51], v[84:87], 0
	s_waitcnt lgkmcnt(8)
	v_mfma_f32_16x16x32_bf16 v[52:55], v[52:55], v[84:87], 0
	ds_read_b64_tr_b16 v[84:85], v205 offset:10240
	ds_read_b64_tr_b16 v[88:89], v205 offset:10272
	ds_read_b64_tr_b16 v[116:117], v205 offset:10304
	ds_read_b64_tr_b16 v[120:121], v205 offset:10336
	ds_read_b64_tr_b16 v[86:87], v205 offset:12800
	ds_read_b64_tr_b16 v[90:91], v205 offset:12832
	ds_read_b64_tr_b16 v[118:119], v205 offset:12864
	ds_read_b64_tr_b16 v[122:123], v205 offset:12896
	v_cvt_pk_bf16_f32 v124, v164, v165
	v_cvt_pk_bf16_f32 v125, v162, v163
	v_cvt_pk_bf16_f32 v126, v160, v161
	v_cvt_pk_bf16_f32 v127, v158, v159
	s_waitcnt lgkmcnt(11)
	s_nop 0
	v_mfma_f32_16x16x32_bf16 v[10:13], v[68:71], v[124:127], v[10:13]
	s_waitcnt lgkmcnt(10)
	v_mfma_f32_16x16x32_bf16 v[14:17], v[72:75], v[124:127], v[14:17]
	s_waitcnt lgkmcnt(9)
	v_mfma_f32_16x16x32_bf16 v[48:51], v[76:79], v[124:127], v[48:51]
	s_waitcnt lgkmcnt(8)
; __device__ __forceinline__ unsigned cvtpk(float lo, float hi) { return pg8::cvt_pk_bf16(lo, hi); }
; __device__ __forceinline__ s16x4 vtr(LAS const unsigned char* p) { return __builtin_bit_cast(s16x4, __builtin_amdgcn_ds_read_tr16_b64_v4i16((LAS s16x4*)p)); }
;     ...
;         for (int c = 0; c < NCH; ++c) { const int b = c & 1;
;             if (c + 1 < NCH) {
; #pragma unroll
;                 for (int d = 0; d < 4; ++d) { vl[b ^ 1][d] = vtr(vp + (32 * (c + 1)) * VRS + d * 32); vh[b ^ 1][d] = vtr(vp + (32 * (c + 1) + 16) * VRS + d * 32); } }
;             v4u pw; pw.x = cvtpk(s[2 * c][0], s[2 * c][1]); pw.y = cvtpk(s[2 * c][2], s[2 * c][3]); pw.z = cvtpk(s[2 * c + 1][0], s[2 * c + 1][1]); pw.w = cvtpk(s[2 * c + 1][2], s[2 * c + 1][3]);
;             const bf16x8 pb = __builtin_bit_cast(bf16x8, pw);
;             __builtin_amdgcn_sched_barrier(0);
; #pragma unroll
;             for (int d = 0; d < 4; ++d) { const s16x4 lo = vl[b][d], hi = vh[b][d];
;                 const bf16x8 va = (bf16x8){lo[0], lo[1], lo[2], lo[3], hi[0], hi[1], hi[2], hi[3]};
;                 o[d] = __builtin_amdgcn_mfma_f32_16x16x32_bf16(va, pb, o[d], 0, 0, 0); }
;             __builtin_amdgcn_sched_barrier(0);
;         }
	v_mfma_f32_16x16x32_bf16 v[52:55], v[80:83], v[124:127], v[52:55]
	ds_read_b64_tr_b16 v[68:69], v205 offset:15360
	ds_read_b64_tr_b16 v[72:73], v205 offset:15392
	ds_read_b64_tr_b16 v[76:77], v205 offset:15424
	ds_read_b64_tr_b16 v[80:81], v205 offset:15456
	ds_read_b64_tr_b16 v[70:71], v205 offset:17920
	ds_read_b64_tr_b16 v[74:75], v205 offset:17952
	ds_read_b64_tr_b16 v[78:79], v205 offset:17984
	ds_read_b64_tr_b16 v[82:83], v205 offset:18016
	v_cvt_pk_bf16_f32 v124, v142, v143
	v_cvt_pk_bf16_f32 v125, v140, v141
	v_cvt_pk_bf16_f32 v126, v138, v139
	v_cvt_pk_bf16_f32 v127, v136, v137
	s_waitcnt lgkmcnt(11)
	s_nop 0
	v_mfma_f32_16x16x32_bf16 v[10:13], v[84:87], v[124:127], v[10:13]
	s_waitcnt lgkmcnt(10)
	v_mfma_f32_16x16x32_bf16 v[14:17], v[88:91], v[124:127], v[14:17]
	s_waitcnt lgkmcnt(9)
	v_mfma_f32_16x16x32_bf16 v[48:51], v[116:119], v[124:127], v[48:51]
	s_waitcnt lgkmcnt(8)
	v_mfma_f32_16x16x32_bf16 v[52:55], v[120:123], v[124:127], v[52:55]
	ds_read_b64_tr_b16 v[84:85], v205 offset:20480
	ds_read_b64_tr_b16 v[88:89], v205 offset:20512
	ds_read_b64_tr_b16 v[116:117], v205 offset:20544
	ds_read_b64_tr_b16 v[120:121], v205 offset:20576
	ds_read_b64_tr_b16 v[86:87], v205 offset:23040
	ds_read_b64_tr_b16 v[90:91], v205 offset:23072
	ds_read_b64_tr_b16 v[118:119], v205 offset:23104
	ds_read_b64_tr_b16 v[122:123], v205 offset:23136
	v_cvt_pk_bf16_f32 v124, v134, v135
	v_cvt_pk_bf16_f32 v125, v132, v133
	v_cvt_pk_bf16_f32 v126, v130, v131
	v_cvt_pk_bf16_f32 v127, v128, v129
	s_waitcnt lgkmcnt(11)
	s_nop 0
	v_mfma_f32_16x16x32_bf16 v[10:13], v[68:71], v[124:127], v[10:13]
	s_waitcnt lgkmcnt(10)
	v_mfma_f32_16x16x32_bf16 v[14:17], v[72:75], v[124:127], v[14:17]
	s_waitcnt lgkmcnt(9)
	v_mfma_f32_16x16x32_bf16 v[48:51], v[76:79], v[124:127], v[48:51]
	s_waitcnt lgkmcnt(8)
	v_mfma_f32_16x16x32_bf16 v[52:55], v[80:83], v[124:127], v[52:55]
	ds_read_b64_tr_b16 v[68:69], v205 offset:25600
	ds_read_b64_tr_b16 v[72:73], v205 offset:25632
	ds_read_b64_tr_b16 v[76:77], v205 offset:25664
	ds_read_b64_tr_b16 v[80:81], v205 offset:25696
	ds_read_b64_tr_b16 v[70:71], v205 offset:28160
	ds_read_b64_tr_b16 v[74:75], v205 offset:28192
	ds_read_b64_tr_b16 v[78:79], v205 offset:28224
	ds_read_b64_tr_b16 v[82:83], v205 offset:28256
	v_cvt_pk_bf16_f32 v124, v172, v173
	v_cvt_pk_bf16_f32 v125, v176, v177
	v_cvt_pk_bf16_f32 v126, v196, v206
	v_cvt_pk_bf16_f32 v127, v207, v208
	s_waitcnt lgkmcnt(11)
	s_nop 0
	v_mfma_f32_16x16x32_bf16 v[10:13], v[84:87], v[124:127], v[10:13]
	s_waitcnt lgkmcnt(10)
	v_mfma_f32_16x16x32_bf16 v[14:17], v[88:91], v[124:127], v[14:17]
	s_waitcnt lgkmcnt(9)
	v_mfma_f32_16x16x32_bf16 v[48:51], v[116:119], v[124:127], v[48:51]
	s_waitcnt lgkmcnt(8)
	v_mfma_f32_16x16x32_bf16 v[52:55], v[120:123], v[124:127], v[52:55]
	ds_read_b64_tr_b16 v[84:85], v205 offset:30720
	ds_read_b64_tr_b16 v[88:89], v205 offset:30752
	ds_read_b64_tr_b16 v[116:117], v205 offset:30784
	ds_read_b64_tr_b16 v[120:121], v205 offset:30816
	ds_read_b64_tr_b16 v[86:87], v205 offset:33280
	ds_read_b64_tr_b16 v[90:91], v205 offset:33312
	ds_read_b64_tr_b16 v[118:119], v205 offset:33344
	ds_read_b64_tr_b16 v[122:123], v205 offset:33376
	v_cvt_pk_bf16_f32 v124, v209, v210
	v_cvt_pk_bf16_f32 v125, v211, v212
	v_cvt_pk_bf16_f32 v126, v213, v214
	v_cvt_pk_bf16_f32 v127, v215, v216
	s_waitcnt lgkmcnt(11)
	s_nop 0
	v_mfma_f32_16x16x32_bf16 v[10:13], v[68:71], v[124:127], v[10:13]
	s_waitcnt lgkmcnt(10)
	v_mfma_f32_16x16x32_bf16 v[14:17], v[72:75], v[124:127], v[14:17]
	s_waitcnt lgkmcnt(9)
	v_mfma_f32_16x16x32_bf16 v[48:51], v[76:79], v[124:127], v[48:51]
	s_waitcnt lgkmcnt(8)
; #define LAS __attribute__((address_space(3)))
; __device__ __forceinline__ unsigned cvtpk(float lo, float hi) { return pg8::cvt_pk_bf16(lo, hi); }
; __device__ __forceinline__ unsigned pk4_fp8(float a, float b, float c, float d) { int r = __builtin_amdgcn_cvt_pk_fp8_f32(a, b, 0, false); r = __builtin_amdgcn_cvt_pk_fp8_f32(c, d, r, true); return (unsigned)r; }
; __device__ __forceinline__ s16x4 vtr(LAS const unsigned char* p) { return __builtin_bit_cast(s16x4, __builtin_amdgcn_ds_read_tr16_b64_v4i16((LAS s16x4*)p)); }
;     ...
;     if (IS_A) sum += __builtin_amdgcn_exp2f(sink2 - m);
;     const float inv = __builtin_amdgcn_rcpf(sum);
;     f32x4 o[4];
; #pragma unroll
;     for (int d = 0; d < 4; ++d) o[d] = (f32x4){0.f, 0.f, 0.f, 0.f};
;     LAS const unsigned char* vp = ldsV + (kstart + 4 * g + (qi >> 2)) * VRS + (qi & 3) * 8;
;     {
;         s16x4 vl[2][4], vh[2][4];
; #pragma unroll
;         for (int d = 0; d < 4; ++d) { vl[0][d] = vtr(vp + d * 32); vh[0][d] = vtr(vp + 16 * VRS + d * 32); }
; #pragma unroll
;         for (int c = 0; c < NCH; ++c) { const int b = c & 1;
;             if (c + 1 < NCH) {
; #pragma unroll
;                 for (int d = 0; d < 4; ++d) { vl[b ^ 1][d] = vtr(vp + (32 * (c + 1)) * VRS + d * 32); vh[b ^ 1][d] = vtr(vp + (32 * (c + 1) + 16) * VRS + d * 32); } }
;             v4u pw; pw.x = cvtpk(s[2 * c][0], s[2 * c][1]); pw.y = cvtpk(s[2 * c][2], s[2 * c][3]); pw.z = cvtpk(s[2 * c + 1][0], s[2 * c + 1][1]); pw.w = cvtpk(s[2 * c + 1][2], s[2 * c + 1][3]);
;             const bf16x8 pb = __builtin_bit_cast(bf16x8, pw);
;             __builtin_amdgcn_sched_barrier(0);
; #pragma unroll
;             for (int d = 0; d < 4; ++d) { const s16x4 lo = vl[b][d], hi = vh[b][d];
;                 const bf16x8 va = (bf16x8){lo[0], lo[1], lo[2], lo[3], hi[0], hi[1], hi[2], hi[3]};
;                 o[d] = __builtin_amdgcn_mfma_f32_16x16x32_bf16(va, pb, o[d], 0, 0, 0); }
;             __builtin_amdgcn_sched_barrier(0);
;         }
;     }
;     if (IS_A) { const float i8 = inv * 8.f;
; #pragma unroll
;         for (int d = 0; d < 4; ++d) *(unsigned*)((unsigned char*)orow + 16 * d + 4 * g) = pk4_fp8(o[d][0] * i8, o[d][1] * i8, o[d][2] * i8, o[d][3] * i8);
	v_mfma_f32_16x16x32_bf16 v[52:55], v[80:83], v[124:127], v[52:55]
	ds_read_b64_tr_b16 v[68:69], v205 offset:35840
	ds_read_b64_tr_b16 v[72:73], v205 offset:35872
	ds_read_b64_tr_b16 v[76:77], v205 offset:35904
	ds_read_b64_tr_b16 v[80:81], v205 offset:35936
	ds_read_b64_tr_b16 v[70:71], v205 offset:38400
	ds_read_b64_tr_b16 v[74:75], v205 offset:38432
	ds_read_b64_tr_b16 v[78:79], v205 offset:38464
	ds_read_b64_tr_b16 v[82:83], v205 offset:38496
	v_cvt_pk_bf16_f32 v124, v217, v218
	v_cvt_pk_bf16_f32 v125, v219, v220
	v_cvt_pk_bf16_f32 v126, v221, v222
	v_cvt_pk_bf16_f32 v127, v223, v224
	s_waitcnt lgkmcnt(11)
	s_nop 0
	v_mfma_f32_16x16x32_bf16 v[10:13], v[84:87], v[124:127], v[10:13]
	s_waitcnt lgkmcnt(10)
	v_mfma_f32_16x16x32_bf16 v[14:17], v[88:91], v[124:127], v[14:17]
	s_waitcnt lgkmcnt(9)
	v_mfma_f32_16x16x32_bf16 v[48:51], v[116:119], v[124:127], v[48:51]
	s_waitcnt lgkmcnt(8)
	v_mfma_f32_16x16x32_bf16 v[52:55], v[120:123], v[124:127], v[52:55]
	ds_read_b64_tr_b16 v[84:85], v205 offset:40960
	ds_read_b64_tr_b16 v[88:89], v205 offset:40992
	ds_read_b64_tr_b16 v[116:117], v205 offset:41024
	ds_read_b64_tr_b16 v[120:121], v205 offset:41056
	ds_read_b64_tr_b16 v[86:87], v205 offset:43520
	ds_read_b64_tr_b16 v[90:91], v205 offset:43552
	ds_read_b64_tr_b16 v[118:119], v205 offset:43584
	ds_read_b64_tr_b16 v[122:123], v205 offset:43616
	v_cvt_pk_bf16_f32 v124, v225, v226
	v_cvt_pk_bf16_f32 v125, v227, v228
	v_cvt_pk_bf16_f32 v126, v229, v230
	v_cvt_pk_bf16_f32 v127, v18, v231
	s_waitcnt lgkmcnt(11)
	s_nop 0
	v_mfma_f32_16x16x32_bf16 v[10:13], v[68:71], v[124:127], v[10:13]
	s_waitcnt lgkmcnt(10)
	v_mfma_f32_16x16x32_bf16 v[14:17], v[72:75], v[124:127], v[14:17]
	s_waitcnt lgkmcnt(9)
	v_mfma_f32_16x16x32_bf16 v[48:51], v[76:79], v[124:127], v[48:51]
	s_waitcnt lgkmcnt(8)
	v_mfma_f32_16x16x32_bf16 v[52:55], v[80:83], v[124:127], v[52:55]
	s_mov_b32 s0, 0x3fb8aa3b
	v_fma_f32 v8, v204, s0, -v8
	v_exp_f32_e32 v8, v8
	v_add_f32_e32 v18, v239, v240
	v_cvt_pk_bf16_f32 v68, v232, v233
	v_cvt_pk_bf16_f32 v69, v234, v235
	v_add_f32_e32 v20, v8, v18
	v_cvt_pk_bf16_f32 v70, v236, v237
	v_cvt_pk_bf16_f32 v71, v9, v238
	s_waitcnt lgkmcnt(3)
	s_nop 0
	v_mfma_f32_16x16x32_bf16 v[8:11], v[84:87], v[68:71], v[10:13]
	s_waitcnt lgkmcnt(2)
	v_mfma_f32_16x16x32_bf16 v[12:15], v[88:91], v[68:71], v[14:17]
	s_waitcnt lgkmcnt(1)
	v_mfma_f32_16x16x32_bf16 v[16:19], v[116:119], v[68:71], v[48:51]
	s_waitcnt lgkmcnt(0)
	v_mfma_f32_16x16x32_bf16 v[48:51], v[120:123], v[68:71], v[52:55]
	v_rcp_f32_e32 v20, v20
	s_nop 1
	v_mov_b32_e32 v54, 0
	v_lshl_add_u64 v[52:53], v[156:157], 0, v[148:149]
	s_mov_b64 s[64:65], 0
	v_mul_f32_e32 v20, 0x41000000, v20
	v_mul_f32_e32 v8, v20, v8
	v_mul_f32_e32 v9, v20, v9
	v_cvt_pk_fp8_f32 v54, v8, v9
	v_mul_f32_e32 v8, v20, v12
	v_mul_f32_e32 v9, v20, v13
	v_mov_b32_e32 v12, 0
	v_cvt_pk_fp8_f32 v12, v8, v9
	v_mul_f32_e32 v8, v20, v14
	v_mul_f32_e32 v9, v20, v15
	v_mov_b32_e32 v13, 0
	v_cvt_pk_fp8_f32 v12, v8, v9 op_sel:[0,0,1]
	v_mul_f32_e32 v8, v20, v16
	v_mul_f32_e32 v9, v20, v17
	v_cvt_pk_fp8_f32 v13, v8, v9
	v_mul_f32_e32 v8, v20, v48
	v_mul_f32_e32 v9, v20, v49
	v_mov_b32_e32 v14, 0
	v_mul_f32_e32 v10, v20, v10
	v_mul_f32_e32 v11, v20, v11
	v_cvt_pk_fp8_f32 v14, v8, v9
	v_cvt_pk_fp8_f32 v54, v10, v11 op_sel:[0,0,1]
	v_mul_f32_e32 v10, v20, v18
	v_mul_f32_e32 v11, v20, v19
	v_cvt_pk_fp8_f32 v13, v10, v11 op_sel:[0,0,1]
	v_mul_f32_e32 v8, v20, v50
	v_mul_f32_e32 v9, v20, v51
	v_cvt_pk_fp8_f32 v14, v8, v9 op_sel:[0,0,1]
	global_store_dword v[52:53], v54, off
	global_store_dword v[52:53], v12, off offset:16
	global_store_dword v[52:53], v13, off offset:32
	global_store_dword v[52:53], v14, off offset:48
	s_waitcnt vmcnt(4)
